# c15_diff_trg2_into_group0_buffers
# speedup vs baseline: 1.0035x; 1.0035x over previous
.Lf_odd_exp:
	v_exp_f32_e32 v82, v114
	v_exp_f32_e32 v83, v115
	ds_read_b64_tr_b16 v[114:115], v1 offset:0x200
	v_exp_f32_e32 v84, v116
	v_exp_f32_e32 v85, v117
	ds_read_b64_tr_b16 v[116:117], v1 offset:0xa00
	v_exp_f32_e32 v86, v118
	v_exp_f32_e32 v87, v119
	ds_read_b64_tr_b16 v[118:119], v1 offset:0x1200
	v_exp_f32_e32 v88, v120
	v_exp_f32_e32 v89, v121
	ds_read_b64_tr_b16 v[120:121], v1 offset:0x1a00
	v_exp_f32_e32 v90, v122
	v_exp_f32_e32 v91, v123
	ds_read_b64_tr_b16 v[122:123], v1 offset:0x2200
	v_exp_f32_e32 v92, v124
	v_exp_f32_e32 v93, v125
	ds_read_b64_tr_b16 v[124:125], v1 offset:0x2a00
	v_exp_f32_e32 v98, v130
	v_exp_f32_e32 v99, v131
	ds_read_b64_tr_b16 v[130:131], v1 offset:0x3200
	v_exp_f32_e32 v100, v132
	v_exp_f32_e32 v101, v133
	ds_read_b64_tr_b16 v[132:133], v1 offset:0x3a00
	s_waitcnt lgkmcnt(8)
	v_mfma_f32_32x32x16_bf16 v[64:79], v[166:169], v[182:185], v[64:79]
	v_exp_f32_e32 v96, v128
	v_exp_f32_e32 v97, v129
	v_mfma_f32_32x32x16_bf16 v[64:79], v[12:15], v[178:181], v[64:79]
	v_exp_f32_e32 v102, v134
	v_exp_f32_e32 v103, v135
	v_mfma_f32_32x32x16_bf16 v[64:79], v[8:11], v[174:177], v[64:79]
	v_exp_f32_e32 v104, v136
	v_exp_f32_e32 v105, v137
	v_mfma_f32_32x32x16_bf16 v[64:79], v[4:7], v[170:173], v[64:79]
	v_exp_f32_e32 v106, v138
	v_exp_f32_e32 v107, v139
	ds_read_b64_tr_b16 v[182:183], v1 offset:0x400
	ds_read_b64_tr_b16 v[184:185], v1 offset:0xc00
	ds_read_b64_tr_b16 v[178:179], v1 offset:0x1400
	ds_read_b64_tr_b16 v[180:181], v1 offset:0x1c00
	ds_read_b64_tr_b16 v[174:175], v1 offset:0x2400
	ds_read_b64_tr_b16 v[176:177], v1 offset:0x2c00
	ds_read_b64_tr_b16 v[170:171], v1 offset:0x3400
	ds_read_b64_tr_b16 v[172:173], v1 offset:0x3c00
	s_waitcnt lgkmcnt(8)
	v_mfma_f32_32x32x16_bf16 v[48:63], v[166:169], v[114:117], v[48:63]
	v_exp_f32_e32 v108, v140
	v_exp_f32_e32 v109, v141
	v_mfma_f32_32x32x16_bf16 v[48:63], v[12:15], v[118:121], v[48:63]
	v_exp_f32_e32 v110, v142
	v_exp_f32_e32 v111, v143
	v_mfma_f32_32x32x16_bf16 v[48:63], v[8:11], v[122:125], v[48:63]
	v_exp_f32_e32 v80, v112
	v_exp_f32_e32 v81, v113
	v_mfma_f32_32x32x16_bf16 v[48:63], v[4:7], v[130:133], v[48:63]
	v_exp_f32_e32 v94, v126
	v_exp_f32_e32 v95, v127
	ds_read_b64_tr_b16 v[114:115], v1 offset:0x600
	ds_read_b64_tr_b16 v[116:117], v1 offset:0xe00
	ds_read_b64_tr_b16 v[118:119], v1 offset:0x1600
	ds_read_b64_tr_b16 v[120:121], v1 offset:0x1e00
	ds_read_b64_tr_b16 v[122:123], v1 offset:0x2600
	ds_read_b64_tr_b16 v[124:125], v1 offset:0x2e00
	ds_read_b64_tr_b16 v[130:131], v1 offset:0x3600
	ds_read_b64_tr_b16 v[132:133], v1 offset:0x3e00
	s_waitcnt lgkmcnt(8)
	v_mfma_f32_32x32x16_bf16 v[32:47], v[166:169], v[182:185], v[32:47]
	v_mfma_f32_32x32x16_bf16 v[32:47], v[12:15], v[178:181], v[32:47]
	v_mfma_f32_32x32x16_bf16 v[32:47], v[8:11], v[174:177], v[32:47]
	v_mfma_f32_32x32x16_bf16 v[32:47], v[4:7], v[170:173], v[32:47]
	s_waitcnt lgkmcnt(0)
	v_mfma_f32_32x32x16_bf16 v[16:31], v[166:169], v[114:117], v[16:31]
	v_mfma_f32_32x32x16_bf16 v[16:31], v[12:15], v[118:121], v[16:31]
	v_mfma_f32_32x32x16_bf16 v[16:31], v[8:11], v[122:125], v[16:31]
	v_mfma_f32_32x32x16_bf16 v[16:31], v[4:7], v[130:133], v[16:31]
	v_cmp_gt_f32_e32 vcc, 1.0, v225
	s_cbranch_vccnz .Lresc_odd_blk

.Lf_even_exp:
	v_exp_f32_e32 v82, v114
	v_exp_f32_e32 v83, v115
	ds_read_b64_tr_b16 v[114:115], v162 offset:0x200
	v_exp_f32_e32 v84, v116
	v_exp_f32_e32 v85, v117
	ds_read_b64_tr_b16 v[116:117], v162 offset:0xa00
	v_exp_f32_e32 v86, v118
	v_exp_f32_e32 v87, v119
	ds_read_b64_tr_b16 v[118:119], v162 offset:0x1200
	v_exp_f32_e32 v88, v120
	v_exp_f32_e32 v89, v121
	ds_read_b64_tr_b16 v[120:121], v162 offset:0x1a00
	v_exp_f32_e32 v90, v122
	v_exp_f32_e32 v91, v123
	ds_read_b64_tr_b16 v[122:123], v162 offset:0x2200
	v_exp_f32_e32 v92, v124
	v_exp_f32_e32 v93, v125
	ds_read_b64_tr_b16 v[124:125], v162 offset:0x2a00
	v_exp_f32_e32 v98, v130
	v_exp_f32_e32 v99, v131
	ds_read_b64_tr_b16 v[130:131], v162 offset:0x3200
	v_exp_f32_e32 v100, v132
	v_exp_f32_e32 v101, v133
	ds_read_b64_tr_b16 v[132:133], v162 offset:0x3a00
	s_waitcnt lgkmcnt(8)
	v_mfma_f32_32x32x16_bf16 v[64:79], v[166:169], v[182:185], v[64:79]
	v_exp_f32_e32 v96, v128
	v_exp_f32_e32 v97, v129
	v_mfma_f32_32x32x16_bf16 v[64:79], v[12:15], v[178:181], v[64:79]
	v_exp_f32_e32 v102, v134
	v_exp_f32_e32 v103, v135
	v_mfma_f32_32x32x16_bf16 v[64:79], v[8:11], v[174:177], v[64:79]
	v_exp_f32_e32 v104, v136
	v_exp_f32_e32 v105, v137
	v_mfma_f32_32x32x16_bf16 v[64:79], v[4:7], v[170:173], v[64:79]
	v_exp_f32_e32 v106, v138
	v_exp_f32_e32 v107, v139
	ds_read_b64_tr_b16 v[182:183], v162 offset:0x400
	ds_read_b64_tr_b16 v[184:185], v162 offset:0xc00
	ds_read_b64_tr_b16 v[178:179], v162 offset:0x1400
	ds_read_b64_tr_b16 v[180:181], v162 offset:0x1c00
	ds_read_b64_tr_b16 v[174:175], v162 offset:0x2400
	ds_read_b64_tr_b16 v[176:177], v162 offset:0x2c00
	ds_read_b64_tr_b16 v[170:171], v162 offset:0x3400
	ds_read_b64_tr_b16 v[172:173], v162 offset:0x3c00
	s_waitcnt lgkmcnt(8)
	v_mfma_f32_32x32x16_bf16 v[48:63], v[166:169], v[114:117], v[48:63]
	v_exp_f32_e32 v108, v140
	v_exp_f32_e32 v109, v141
	v_mfma_f32_32x32x16_bf16 v[48:63], v[12:15], v[118:121], v[48:63]
	v_exp_f32_e32 v110, v142
	v_exp_f32_e32 v111, v143
	v_mfma_f32_32x32x16_bf16 v[48:63], v[8:11], v[122:125], v[48:63]
	v_exp_f32_e32 v80, v112
	v_exp_f32_e32 v81, v113
	v_mfma_f32_32x32x16_bf16 v[48:63], v[4:7], v[130:133], v[48:63]
	v_exp_f32_e32 v94, v126
	v_exp_f32_e32 v95, v127
	ds_read_b64_tr_b16 v[114:115], v162 offset:0x600
	ds_read_b64_tr_b16 v[116:117], v162 offset:0xe00
	ds_read_b64_tr_b16 v[118:119], v162 offset:0x1600
	ds_read_b64_tr_b16 v[120:121], v162 offset:0x1e00
	ds_read_b64_tr_b16 v[122:123], v162 offset:0x2600
	ds_read_b64_tr_b16 v[124:125], v162 offset:0x2e00
	ds_read_b64_tr_b16 v[130:131], v162 offset:0x3600
	ds_read_b64_tr_b16 v[132:133], v162 offset:0x3e00
	s_waitcnt lgkmcnt(8)
	v_mfma_f32_32x32x16_bf16 v[32:47], v[166:169], v[182:185], v[32:47]
	v_mfma_f32_32x32x16_bf16 v[32:47], v[12:15], v[178:181], v[32:47]
	v_mfma_f32_32x32x16_bf16 v[32:47], v[8:11], v[174:177], v[32:47]
	v_mfma_f32_32x32x16_bf16 v[32:47], v[4:7], v[170:173], v[32:47]
	s_waitcnt lgkmcnt(0)
	v_mfma_f32_32x32x16_bf16 v[16:31], v[166:169], v[114:117], v[16:31]
	v_mfma_f32_32x32x16_bf16 v[16:31], v[12:15], v[118:121], v[16:31]
	v_mfma_f32_32x32x16_bf16 v[16:31], v[8:11], v[122:125], v[16:31]
	v_mfma_f32_32x32x16_bf16 v[16:31], v[4:7], v[130:133], v[16:31]
	v_cmp_gt_f32_e32 vcc, 1.0, v196
	s_cbranch_vccnz .Lresc_even_blk
